# lru tile x-row loads batched in both passes (17 dependent round trips -> 1), scalar row-validity tests
# speedup vs baseline: 1.1610x; 1.0256x over previous
; DI float bf2f(bfr b) { return __uint_as_float(((unsigned)b) << 16); }
; DI void lru_tile(const Params& p, int layer, int isP, int sq, int tile, int nb, int pass, char*) {
;     ...
; #pragma unroll
;   for (int nt = 0; nt < 4; ++nt) {
;     const int d = nt * 16 + fr;
;     wfa0[nt] = *(const bf16x8*)(WaT + d * 64 + fq * 8); wfa1[nt] = *(const bf16x8*)(WaT + d * 64 + 32 + fq * 8);
;     wfx0[nt] = *(const bf16x8*)(WxT + d * 64 + fq * 8); wfx1[nt] = *(const bf16x8*)(WxT + d * 64 + 32 + fq * 8);
;     pbav[nt] = p.lru_ba[layer * 512 + ch0 + d]; pbxv[nt] = p.lru_bx[layer * 512 + ch0 + d];
;     plam[nt] = p.lru_lambda[layer * 512 + ch0 + d];
;   }
;   const float pcb = p.conv_b[layer * 512 + ch0 + (tid & 63)];
;   const float pw0 = p.conv_w[(layer * 4 + 0) * 512 + ch0 + (tid & 63)], pw1 = p.conv_w[(layer * 4 + 1) * 512 + ch0 + (tid & 63)],
;               pw2 = p.conv_w[(layer * 4 + 2) * 512 + ch0 + (tid & 63)], pw3 = p.conv_w[(layer * 4 + 3) * 512 + ch0 + (tid & 63)];
;   {
;     const int c = tid & 63;
;     float vv[17];
; #pragma unroll
;     for (int i = 0; i < 17; ++i) {
;       const int rr = i * 4 + (tid >> 6);
;       const int tt = t0 - 3 + rr;
;       float v = 0.f;
;       if (rr < 67) {
;         if (tt < 0) { if (!isP) v = p.state_conv[((long)(layer * NB_S + sq) * 3 + (3 + tt)) * 512 + ch0 + c]; }
;         else if (tt < T) v = bf2f(xbb[(long)(rowbase + tt) * 512 + ch0 + c]);
;       }
;       vv[i] = v;
;     }
.LBB0_2624:
	s_andn2_b64 vcc, exec, s[0:1]
	s_cbranch_vccnz .LBB0_2706
	s_add_i32 s0, s60, 0xfbbc
	s_and_b32 s1, s0, 0xffff
	s_mulk_i32 s1, 0xfc1
	s_lshr_b32 s36, s1, 21
	s_mul_i32 s1, s36, 0x208
	s_sub_i32 s0, s0, s1
	s_lshr_b32 s1, s0, 3
	s_and_b32 s6, s0, 7
	v_readlane_b32 s0, v251, 51
	s_or_b32 s0, s6, s0
	s_and_b32 s37, s1, 0x1fff
	s_ashr_i32 s1, s0, 31
	v_mov_b32_e32 v94, v158
	s_lshl_b32 s38, s6, 6
	s_lshl_b64 s[0:1], s[0:1], 13
	v_readlane_b32 s2, v251, 59
	s_add_u32 s2, s2, s0
	v_and_b32_e32 v74, 15, v94
	v_readlane_b32 s3, v251, 60
	s_addc_u32 s3, s3, s1
	v_readlane_b32 s4, v251, 61
	v_lshlrev_b32_e32 v128, 7, v74
	s_add_u32 s0, s4, s0
	v_readlane_b32 s4, v251, 62
	v_lshl_add_u64 v[0:1], s[2:3], 0, v[128:129]
	v_and_b32_e32 v2, 48, v94
	v_mov_b32_e32 v3, v129
	s_addc_u32 s1, s4, s1
	v_lshl_add_u64 v[0:1], v[0:1], 0, v[2:3]
	v_readlane_b32 s4, v251, 50
	global_load_dwordx4 v[56:59], v[0:1], off
	global_load_dwordx4 v[48:51], v[0:1], off offset:64
	v_lshl_add_u64 v[0:1], s[0:1], 0, v[128:129]
	s_or_b32 s4, s38, s4
	v_lshl_add_u64 v[0:1], v[0:1], 0, v[2:3]
	global_load_dwordx4 v[60:63], v[0:1], off
	global_load_dwordx4 v[52:55], v[0:1], off offset:64
	v_or_b32_e32 v0, s4, v74
	v_readlane_b32 s8, v249, 22
	v_ashrrev_i32_e32 v1, 31, v0
	v_readlane_b32 s12, v249, 26
	v_readlane_b32 s13, v249, 27
	v_readlane_b32 s16, v249, 30
	v_readlane_b32 s17, v249, 31
	v_readlane_b32 s20, v249, 34
	v_readlane_b32 s21, v249, 35
	v_lshlrev_b64 v[0:1], 2, v[0:1]
	s_mov_b64 s[12:13], s[16:17]
	s_mov_b64 s[16:17], s[20:21]
	v_readlane_b32 s40, v249, 38
	s_waitcnt vmcnt(4)
	v_lshl_add_u64 v[4:5], s[16:17], 0, v[0:1]
	v_readlane_b32 s41, v249, 39
	v_readlane_b32 s42, v249, 40
	v_readlane_b32 s43, v249, 41
	global_load_dword v91, v[4:5], off
	v_lshl_add_u64 v[4:5], s[40:41], 0, v[0:1]
	v_lshl_add_u64 v[0:1], s[42:43], 0, v[0:1]
	global_load_dword v95, v[0:1], off
	v_or_b32_e32 v0, 0x800, v128
	v_mov_b32_e32 v1, v129
	global_load_dword v92, v[4:5], off
	v_lshl_add_u64 v[4:5], s[2:3], 0, v[0:1]
	v_lshl_add_u64 v[0:1], s[0:1], 0, v[0:1]
	v_lshl_add_u64 v[4:5], v[4:5], 0, v[2:3]
	v_lshl_add_u64 v[0:1], v[0:1], 0, v[2:3]
	s_ashr_i32 s5, s4, 31
	v_mov_b32_e32 v75, v129
	global_load_dwordx4 v[44:47], v[4:5], off
	global_load_dwordx4 v[40:43], v[4:5], off offset:64
	global_load_dwordx4 v[36:39], v[0:1], off
	global_load_dwordx4 v[32:35], v[0:1], off offset:64
	v_lshl_add_u64 v[0:1], v[74:75], 0, s[4:5]
	v_lshlrev_b64 v[0:1], 2, v[0:1]
	v_lshl_add_u64 v[64:65], s[16:17], 0, v[0:1]
	v_lshl_add_u64 v[66:67], s[40:41], 0, v[0:1]
	v_lshl_add_u64 v[68:69], s[42:43], 0, v[0:1]
	v_or_b32_e32 v0, 0x1000, v128
	v_mov_b32_e32 v1, v129
	v_lshl_add_u64 v[4:5], s[2:3], 0, v[0:1]
	v_lshl_add_u64 v[0:1], s[0:1], 0, v[0:1]
	v_lshl_add_u64 v[4:5], v[4:5], 0, v[2:3]
	v_lshl_add_u64 v[0:1], v[0:1], 0, v[2:3]
	v_or_b32_e32 v128, 0x1800, v128
	global_load_dwordx4 v[28:31], v[4:5], off
	global_load_dwordx4 v[24:27], v[4:5], off offset:64
	global_load_dwordx4 v[20:23], v[0:1], off
	global_load_dwordx4 v[16:19], v[0:1], off offset:64
	v_lshl_add_u64 v[0:1], s[2:3], 0, v[128:129]
	v_lshl_add_u64 v[0:1], v[0:1], 0, v[2:3]
	global_load_dwordx4 v[12:15], v[0:1], off
	global_load_dwordx4 v[8:11], v[0:1], off offset:64
	v_lshl_add_u64 v[0:1], s[0:1], 0, v[128:129]
	v_lshl_add_u64 v[0:1], v[0:1], 0, v[2:3]
	global_load_dwordx4 v[4:7], v[0:1], off
	s_nop 0
	global_load_dwordx4 v[0:3], v[0:1], off offset:64
	s_nop 0
	global_load_dword v90, v[64:65], off offset:64
	global_load_dword v87, v[64:65], off offset:128
	global_load_dword v84, v[64:65], off offset:192
	global_load_dword v89, v[66:67], off offset:64
	global_load_dword v86, v[66:67], off offset:128
	global_load_dword v75, v[66:67], off offset:192
	global_load_dword v93, v[68:69], off offset:64
	global_load_dword v88, v[68:69], off offset:128
	global_load_dword v85, v[68:69], off offset:192
	v_readlane_b32 s0, v251, 52
	v_and_b32_e32 v72, 63, v94
	s_or_b32 s0, s38, s0
	v_readlane_b32 s10, v249, 24
	v_readlane_b32 s11, v249, 25
	v_readlane_b32 s14, v249, 28
	v_readlane_b32 s15, v249, 29
	v_or_b32_e32 v66, s0, v72
	s_mov_b64 s[10:11], s[14:15]
	v_or_b32_e32 v64, s4, v72
	v_ashrrev_i32_e32 v67, 31, v66
	v_ashrrev_i32_e32 v65, 31, v64
	v_lshl_add_u64 v[68:69], v[66:67], 2, s[10:11]
	s_movk_i32 s0, 0x1000
	v_lshl_add_u64 v[64:65], v[64:65], 2, s[12:13]
	v_add_co_u32_e32 v76, vcc, s0, v68
	global_load_dword v64, v[64:65], off
	s_nop 0
	v_addc_co_u32_e32 v77, vcc, 0, v69, vcc
	global_load_dword v66, v[68:69], off
	s_nop 0
	global_load_dword v68, v[68:69], off offset:2048
	s_nop 0
	global_load_dword v70, v[76:77], off
	s_nop 0
	global_load_dword v76, v[76:77], off offset:2048
	s_lshl_b32 s40, s37, 6
	s_add_i32 s34, s40, -3
	s_lshl_b32 s0, s6, 7
	v_readlane_b32 s1, v251, 63
	s_add_u32 s0, s1, s0
	v_readlane_b32 s1, v252, 0
	v_ashrrev_i32_e32 v78, 6, v94
	s_addc_u32 s1, s1, 0
	v_lshlrev_b32_e32 v128, 1, v72
	v_lshl_add_u64 v[80:81], s[0:1], 0, v[128:129]
	v_readfirstlane_b32 s39, v78
	s_mul_i32 s41, s36, 0x1010
	v_add_u32_e32 v79, 4, v78
	s_add_i32 s2, s34, s39
	s_add_i32 s4, s2, s41
	s_add_i32 s4, s4, 4
	s_ashr_i32 s5, s4, 31
	s_lshl_b64 s[4:5], s[4:5], 10
	v_mov_b32_e32 v115, s5
	v_add_co_u32_e32 v114, vcc, s4, v80
	s_nop 1
	v_addc_co_u32_e32 v115, vcc, v115, v81, vcc
	v_mov_b32_e32 v97, 0
	v_mov_b32_e32 v98, 0
	v_mov_b32_e32 v99, 0
	v_mov_b32_e32 v100, 0
	v_mov_b32_e32 v101, 0
	v_mov_b32_e32 v102, 0
	v_mov_b32_e32 v103, 0
	v_mov_b32_e32 v104, 0
	v_mov_b32_e32 v105, 0
	v_mov_b32_e32 v106, 0
	v_mov_b32_e32 v107, 0
	v_mov_b32_e32 v108, 0
	v_mov_b32_e32 v109, 0
	v_mov_b32_e32 v110, 0
	v_mov_b32_e32 v111, 0
	v_mov_b32_e32 v112, 0
	v_mov_b32_e32 v113, 0
	s_cmp_lt_u32 s2, s92
	s_cbranch_scc0 .Llx0_n0
	global_load_ushort v97, v[114:115], off offset:-4096
; DI float bf2f(bfr b) { return __uint_as_float(((unsigned)b) << 16); }
; DI void lru_tile(const Params& p, int layer, int isP, int sq, int tile, int nb, int pass, char*) {
;     ...
;   {
;     const int c = tid & 63;
;     float vv[17];
; #pragma unroll
;     for (int i = 0; i < 17; ++i) {
;       const int rr = i * 4 + (tid >> 6);
;       const int tt = t0 - 3 + rr;
;       float v = 0.f;
;       if (rr < 67) {
;         if (tt < 0) { if (!isP) v = p.state_conv[((long)(layer * NB_S + sq) * 3 + (3 + tt)) * 512 + ch0 + c]; }
;         else if (tt < T) v = bf2f(xbb[(long)(rowbase + tt) * 512 + ch0 + c]);
;       }
;       vv[i] = v;
;     }
; #pragma unroll
;     for (int i = 0; i < 17; ++i) { const int rr = i * 4 + (tid >> 6); if (rr < 67) xbs[rr * 64 + c] = vv[i]; }
;   }
.Llx0_n0:
	s_add_i32 s2, s2, 4
	s_cmp_lt_u32 s2, s92
	s_cbranch_scc0 .Llx0_n1
	global_load_ushort v98, v[114:115], off
.Llx0_n1:
	s_add_i32 s2, s2, 4
	v_add_co_u32_e32 v114, vcc, 0x2000, v114
	s_nop 1
	v_addc_co_u32_e32 v115, vcc, 0, v115, vcc
	s_cmp_lt_u32 s2, s92
	s_cbranch_scc0 .Llx0_n2
	global_load_ushort v99, v[114:115], off offset:-4096
.Llx0_n2:
	s_add_i32 s2, s2, 4
	s_cmp_lt_u32 s2, s92
	s_cbranch_scc0 .Llx0_n3
	global_load_ushort v100, v[114:115], off
.Llx0_n3:
	s_add_i32 s2, s2, 4
	v_add_co_u32_e32 v114, vcc, 0x2000, v114
	s_nop 1
	v_addc_co_u32_e32 v115, vcc, 0, v115, vcc
	s_cmp_lt_u32 s2, s92
	s_cbranch_scc0 .Llx0_n4
	global_load_ushort v101, v[114:115], off offset:-4096
.Llx0_n4:
	s_add_i32 s2, s2, 4
	s_cmp_lt_u32 s2, s92
	s_cbranch_scc0 .Llx0_n5
	global_load_ushort v102, v[114:115], off
.Llx0_n5:
	s_add_i32 s2, s2, 4
	v_add_co_u32_e32 v114, vcc, 0x2000, v114
	s_nop 1
	v_addc_co_u32_e32 v115, vcc, 0, v115, vcc
	s_cmp_lt_u32 s2, s92
	s_cbranch_scc0 .Llx0_n6
	global_load_ushort v103, v[114:115], off offset:-4096
.Llx0_n6:
	s_add_i32 s2, s2, 4
	s_cmp_lt_u32 s2, s92
	s_cbranch_scc0 .Llx0_n7
	global_load_ushort v104, v[114:115], off
.Llx0_n7:
	s_add_i32 s2, s2, 4
	v_add_co_u32_e32 v114, vcc, 0x2000, v114
	s_nop 1
	v_addc_co_u32_e32 v115, vcc, 0, v115, vcc
	s_cmp_lt_u32 s2, s92
	s_cbranch_scc0 .Llx0_n8
	global_load_ushort v105, v[114:115], off offset:-4096
.Llx0_n8:
	s_add_i32 s2, s2, 4
	s_cmp_lt_u32 s2, s92
	s_cbranch_scc0 .Llx0_n9
	global_load_ushort v106, v[114:115], off
.Llx0_n9:
	s_add_i32 s2, s2, 4
	v_add_co_u32_e32 v114, vcc, 0x2000, v114
	s_nop 1
	v_addc_co_u32_e32 v115, vcc, 0, v115, vcc
	s_cmp_lt_u32 s2, s92
	s_cbranch_scc0 .Llx0_n10
	global_load_ushort v107, v[114:115], off offset:-4096
.Llx0_n10:
	s_add_i32 s2, s2, 4
	s_cmp_lt_u32 s2, s92
	s_cbranch_scc0 .Llx0_n11
	global_load_ushort v108, v[114:115], off
.Llx0_n11:
	s_add_i32 s2, s2, 4
	v_add_co_u32_e32 v114, vcc, 0x2000, v114
	s_nop 1
	v_addc_co_u32_e32 v115, vcc, 0, v115, vcc
	s_cmp_lt_u32 s2, s92
	s_cbranch_scc0 .Llx0_n12
	global_load_ushort v109, v[114:115], off offset:-4096
.Llx0_n12:
	s_add_i32 s2, s2, 4
	s_cmp_lt_u32 s2, s92
	s_cbranch_scc0 .Llx0_n13
	global_load_ushort v110, v[114:115], off
.Llx0_n13:
	s_add_i32 s2, s2, 4
	v_add_co_u32_e32 v114, vcc, 0x2000, v114
	s_nop 1
	v_addc_co_u32_e32 v115, vcc, 0, v115, vcc
	s_cmp_lt_u32 s2, s92
	s_cbranch_scc0 .Llx0_n14
	global_load_ushort v111, v[114:115], off offset:-4096
.Llx0_n14:
	s_add_i32 s2, s2, 4
	s_cmp_lt_u32 s2, s92
	s_cbranch_scc0 .Llx0_n15
	global_load_ushort v112, v[114:115], off
.Llx0_n15:
	s_add_i32 s2, s2, 4
	v_add_co_u32_e32 v114, vcc, 0x2000, v114
	s_nop 1
	v_addc_co_u32_e32 v115, vcc, 0, v115, vcc
	s_cmp_lt_u32 s39, 3
	s_cbranch_scc0 .Llx0_n16
	s_cmp_lt_u32 s2, s92
	s_cbranch_scc0 .Llx0_n16
	global_load_ushort v113, v[114:115], off offset:-4096
.Llx0_n16:
	s_add_i32 s2, s2, 4
	s_waitcnt vmcnt(0)
	v_lshl_add_u32 v116, v72, 2, v169
	v_lshl_add_u32 v116, v78, 8, v116
	v_lshlrev_b32_e32 v97, 16, v97
	ds_write_b32 v116, v97
	v_lshlrev_b32_e32 v98, 16, v98
	ds_write_b32 v116, v98 offset:1024
	v_lshlrev_b32_e32 v99, 16, v99
	ds_write_b32 v116, v99 offset:2048
	v_lshlrev_b32_e32 v100, 16, v100
	ds_write_b32 v116, v100 offset:3072
	v_lshlrev_b32_e32 v101, 16, v101
	ds_write_b32 v116, v101 offset:4096
	v_lshlrev_b32_e32 v102, 16, v102
	ds_write_b32 v116, v102 offset:5120
	v_lshlrev_b32_e32 v103, 16, v103
	ds_write_b32 v116, v103 offset:6144
	v_lshlrev_b32_e32 v104, 16, v104
	ds_write_b32 v116, v104 offset:7168
	v_lshlrev_b32_e32 v105, 16, v105
	ds_write_b32 v116, v105 offset:8192
	v_lshlrev_b32_e32 v106, 16, v106
	ds_write_b32 v116, v106 offset:9216
	v_lshlrev_b32_e32 v107, 16, v107
	ds_write_b32 v116, v107 offset:10240
	v_lshlrev_b32_e32 v108, 16, v108
	ds_write_b32 v116, v108 offset:11264
	v_lshlrev_b32_e32 v109, 16, v109
	ds_write_b32 v116, v109 offset:12288
	v_lshlrev_b32_e32 v110, 16, v110
	ds_write_b32 v116, v110 offset:13312
	v_lshlrev_b32_e32 v111, 16, v111
	ds_write_b32 v116, v111 offset:14336
	v_lshlrev_b32_e32 v112, 16, v112
	ds_write_b32 v116, v112 offset:15360
	s_cmp_lt_u32 s39, 3
	s_cbranch_scc0 .Llx0_done
	v_lshlrev_b32_e32 v113, 16, v113
	ds_write_b32 v116, v113 offset:16384
.Llx0_done:
	v_lshl_add_u32 v81, v72, 2, v169
	s_mov_b64 s[0:1], -1

; DI float bf2f(bfr b) { return __uint_as_float(((unsigned)b) << 16); }
; DI void lru_tile(const Params& p, int layer, int isP, int sq, int tile, int nb, int pass, char*) {
;     ...
; #pragma unroll
;   for (int nt = 0; nt < 4; ++nt) {
;     const int d = nt * 16 + fr;
;     wfa0[nt] = *(const bf16x8*)(WaT + d * 64 + fq * 8); wfa1[nt] = *(const bf16x8*)(WaT + d * 64 + 32 + fq * 8);
;     wfx0[nt] = *(const bf16x8*)(WxT + d * 64 + fq * 8); wfx1[nt] = *(const bf16x8*)(WxT + d * 64 + 32 + fq * 8);
;     pbav[nt] = p.lru_ba[layer * 512 + ch0 + d]; pbxv[nt] = p.lru_bx[layer * 512 + ch0 + d];
;     plam[nt] = p.lru_lambda[layer * 512 + ch0 + d];
;   }
;   const float pcb = p.conv_b[layer * 512 + ch0 + (tid & 63)];
;   const float pw0 = p.conv_w[(layer * 4 + 0) * 512 + ch0 + (tid & 63)], pw1 = p.conv_w[(layer * 4 + 1) * 512 + ch0 + (tid & 63)],
;               pw2 = p.conv_w[(layer * 4 + 2) * 512 + ch0 + (tid & 63)], pw3 = p.conv_w[(layer * 4 + 3) * 512 + ch0 + (tid & 63)];
;   {
;     const int c = tid & 63;
;     float vv[17];
; #pragma unroll
;     for (int i = 0; i < 17; ++i) {
;       const int rr = i * 4 + (tid >> 6);
;       const int tt = t0 - 3 + rr;
;       float v = 0.f;
;       if (rr < 67) {
;         if (tt < 0) { if (!isP) v = p.state_conv[((long)(layer * NB_S + sq) * 3 + (3 + tt)) * 512 + ch0 + c]; }
;         else if (tt < T) v = bf2f(xbb[(long)(rowbase + tt) * 512 + ch0 + c]);
;       }
;       vv[i] = v;
;     }
.LBB0_4680:
	s_and_b64 vcc, exec, s[0:1]
	s_cbranch_vccz .LBB0_4487
	s_mul_hi_i32 s0, s65, 0x7e07e07f
	s_lshr_b32 s1, s0, 31
	s_ashr_i32 s42, s0, 8
	s_add_i32 s42, s42, s1
	s_mul_i32 s0, s42, 0x208
	s_sub_i32 s0, s65, s0
	s_and_b32 s6, s0, 7
	s_ashr_i32 s45, s0, 3
	s_or_b32 s0, s6, s41
	s_ashr_i32 s1, s0, 31
	v_mov_b32_e32 v95, v158
	s_lshl_b32 s43, s6, 6
	s_lshl_b64 s[0:1], s[0:1], 13
	s_add_u32 s2, s57, s0
	v_and_b32_e32 v74, 15, v95
	s_addc_u32 s3, s58, s1
	v_lshlrev_b32_e32 v128, 7, v74
	s_add_u32 s0, s59, s0
	v_lshl_add_u64 v[0:1], s[2:3], 0, v[128:129]
	v_and_b32_e32 v2, 48, v95
	v_mov_b32_e32 v3, v129
	s_addc_u32 s1, s60, s1
	v_lshl_add_u64 v[0:1], v[0:1], 0, v[2:3]
	global_load_dwordx4 v[56:59], v[0:1], off
	global_load_dwordx4 v[48:51], v[0:1], off offset:64
	v_lshl_add_u64 v[0:1], s[0:1], 0, v[128:129]
	s_or_b32 s4, s43, s52
	v_lshl_add_u64 v[0:1], v[0:1], 0, v[2:3]
	global_load_dwordx4 v[60:63], v[0:1], off
	global_load_dwordx4 v[52:55], v[0:1], off offset:64
	v_or_b32_e32 v0, s4, v74
	v_readlane_b32 s8, v249, 22
	v_ashrrev_i32_e32 v1, 31, v0
	v_readlane_b32 s12, v249, 26
	v_readlane_b32 s13, v249, 27
	v_readlane_b32 s16, v249, 30
	v_readlane_b32 s17, v249, 31
	v_readlane_b32 s20, v249, 34
	v_readlane_b32 s21, v249, 35
	v_lshlrev_b64 v[0:1], 2, v[0:1]
	s_mov_b64 s[12:13], s[16:17]
	s_mov_b64 s[16:17], s[20:21]
	v_readlane_b32 s64, v249, 38
	s_waitcnt vmcnt(4)
	v_lshl_add_u64 v[4:5], s[16:17], 0, v[0:1]
	v_readlane_b32 s65, v249, 39
	v_readlane_b32 s66, v249, 40
	v_readlane_b32 s67, v249, 41
	global_load_dword v92, v[4:5], off
	v_lshl_add_u64 v[4:5], s[64:65], 0, v[0:1]
	v_lshl_add_u64 v[0:1], s[66:67], 0, v[0:1]
	global_load_dword v96, v[0:1], off
	v_or_b32_e32 v0, 0x800, v128
	v_mov_b32_e32 v1, v129
	global_load_dword v93, v[4:5], off
	v_lshl_add_u64 v[4:5], s[2:3], 0, v[0:1]
	v_lshl_add_u64 v[0:1], s[0:1], 0, v[0:1]
	v_lshl_add_u64 v[4:5], v[4:5], 0, v[2:3]
	v_lshl_add_u64 v[0:1], v[0:1], 0, v[2:3]
	s_ashr_i32 s5, s4, 31
	v_mov_b32_e32 v75, v129
	global_load_dwordx4 v[44:47], v[4:5], off
	global_load_dwordx4 v[40:43], v[4:5], off offset:64
	global_load_dwordx4 v[36:39], v[0:1], off
	global_load_dwordx4 v[32:35], v[0:1], off offset:64
	v_lshl_add_u64 v[0:1], v[74:75], 0, s[4:5]
	v_lshlrev_b64 v[0:1], 2, v[0:1]
	v_lshl_add_u64 v[64:65], s[16:17], 0, v[0:1]
	v_lshl_add_u64 v[66:67], s[64:65], 0, v[0:1]
	v_lshl_add_u64 v[68:69], s[66:67], 0, v[0:1]
	v_or_b32_e32 v0, 0x1000, v128
	v_mov_b32_e32 v1, v129
	v_lshl_add_u64 v[4:5], s[2:3], 0, v[0:1]
	v_lshl_add_u64 v[0:1], s[0:1], 0, v[0:1]
	v_lshl_add_u64 v[4:5], v[4:5], 0, v[2:3]
	v_lshl_add_u64 v[0:1], v[0:1], 0, v[2:3]
	v_or_b32_e32 v128, 0x1800, v128
	global_load_dwordx4 v[28:31], v[4:5], off
	global_load_dwordx4 v[24:27], v[4:5], off offset:64
	global_load_dwordx4 v[20:23], v[0:1], off
	global_load_dwordx4 v[16:19], v[0:1], off offset:64
	v_lshl_add_u64 v[0:1], s[2:3], 0, v[128:129]
	v_lshl_add_u64 v[0:1], v[0:1], 0, v[2:3]
	global_load_dwordx4 v[12:15], v[0:1], off
	global_load_dwordx4 v[8:11], v[0:1], off offset:64
	v_lshl_add_u64 v[0:1], s[0:1], 0, v[128:129]
	v_lshl_add_u64 v[0:1], v[0:1], 0, v[2:3]
	global_load_dwordx4 v[4:7], v[0:1], off
	s_nop 0
	global_load_dwordx4 v[0:3], v[0:1], off offset:64
	s_nop 0
	global_load_dword v91, v[64:65], off offset:64
	global_load_dword v88, v[64:65], off offset:128
	global_load_dword v85, v[64:65], off offset:192
	global_load_dword v90, v[66:67], off offset:64
	global_load_dword v87, v[66:67], off offset:128
	global_load_dword v84, v[66:67], off offset:192
	global_load_dword v94, v[68:69], off offset:64
	global_load_dword v89, v[68:69], off offset:128
	global_load_dword v86, v[68:69], off offset:192
	v_and_b32_e32 v72, 63, v95
	v_or_b32_e32 v75, s43, v72
	v_readlane_b32 s10, v249, 24
	v_readlane_b32 s11, v249, 25
	v_readlane_b32 s14, v249, 28
	v_readlane_b32 s15, v249, 29
	v_or_b32_e32 v66, s53, v75
	s_mov_b64 s[10:11], s[14:15]
	v_or_b32_e32 v64, s4, v72
	v_ashrrev_i32_e32 v67, 31, v66
	v_ashrrev_i32_e32 v65, 31, v64
	v_lshl_add_u64 v[68:69], v[66:67], 2, s[10:11]
	s_movk_i32 s0, 0x1000
	v_lshl_add_u64 v[64:65], v[64:65], 2, s[12:13]
	v_add_co_u32_e32 v76, vcc, s0, v68
	global_load_dword v64, v[64:65], off
	s_nop 0
	v_addc_co_u32_e32 v77, vcc, 0, v69, vcc
	global_load_dword v66, v[68:69], off
	s_nop 0
	global_load_dword v68, v[68:69], off offset:2048
	s_nop 0
	global_load_dword v70, v[76:77], off
	s_nop 0
	global_load_dword v76, v[76:77], off offset:2048
	s_lshl_b32 s44, s45, 6
	s_add_i32 s34, s44, -3
	s_lshl_b32 s0, s6, 7
	s_add_u32 s0, s61, s0
	v_ashrrev_i32_e32 v78, 6, v95
	s_addc_u32 s1, s62, 0
	v_lshlrev_b32_e32 v128, 1, v72
	v_lshl_add_u64 v[80:81], s[0:1], 0, v[128:129]
	v_readfirstlane_b32 s47, v78
	s_mul_i32 s46, s42, 0x1010
	v_add_u32_e32 v79, 4, v78
	s_movk_i32 s64, 0x90
	s_add_i32 s2, s34, s47
	s_add_i32 s4, s2, s46
	s_add_i32 s4, s4, 4
	s_ashr_i32 s5, s4, 31
	s_lshl_b64 s[4:5], s[4:5], 10
	v_mov_b32_e32 v117, s5
	v_add_co_u32_e32 v116, vcc, s4, v80
	s_nop 1
	v_addc_co_u32_e32 v117, vcc, v117, v81, vcc
	v_mov_b32_e32 v98, 0
	v_mov_b32_e32 v99, 0
	v_mov_b32_e32 v100, 0
	v_mov_b32_e32 v101, 0
	v_mov_b32_e32 v102, 0
	v_mov_b32_e32 v103, 0
	v_mov_b32_e32 v104, 0
	v_mov_b32_e32 v105, 0
	v_mov_b32_e32 v106, 0
	v_mov_b32_e32 v107, 0
	v_mov_b32_e32 v108, 0
	v_mov_b32_e32 v109, 0
	v_mov_b32_e32 v110, 0
	v_mov_b32_e32 v111, 0
	v_mov_b32_e32 v112, 0
	v_mov_b32_e32 v113, 0
	v_mov_b32_e32 v114, 0
	s_cmp_lt_u32 s2, s92
	s_cbranch_scc0 .Llx1_n0
	global_load_ushort v98, v[116:117], off offset:-4096
; DI float bf2f(bfr b) { return __uint_as_float(((unsigned)b) << 16); }
; DI void lru_tile(const Params& p, int layer, int isP, int sq, int tile, int nb, int pass, char*) {
;     ...
;   {
;     const int c = tid & 63;
;     float vv[17];
; #pragma unroll
;     for (int i = 0; i < 17; ++i) {
;       const int rr = i * 4 + (tid >> 6);
;       const int tt = t0 - 3 + rr;
;       float v = 0.f;
;       if (rr < 67) {
;         if (tt < 0) { if (!isP) v = p.state_conv[((long)(layer * NB_S + sq) * 3 + (3 + tt)) * 512 + ch0 + c]; }
;         else if (tt < T) v = bf2f(xbb[(long)(rowbase + tt) * 512 + ch0 + c]);
;       }
;       vv[i] = v;
;     }
; #pragma unroll
;     for (int i = 0; i < 17; ++i) { const int rr = i * 4 + (tid >> 6); if (rr < 67) xbs[rr * 64 + c] = vv[i]; }
;   }
.Llx1_n0:
	s_add_i32 s2, s2, 4
	s_cmp_lt_u32 s2, s92
	s_cbranch_scc0 .Llx1_n1
	global_load_ushort v99, v[116:117], off
.Llx1_n1:
	s_add_i32 s2, s2, 4
	v_add_co_u32_e32 v116, vcc, 0x2000, v116
	s_nop 1
	v_addc_co_u32_e32 v117, vcc, 0, v117, vcc
	s_cmp_lt_u32 s2, s92
	s_cbranch_scc0 .Llx1_n2
	global_load_ushort v100, v[116:117], off offset:-4096
.Llx1_n2:
	s_add_i32 s2, s2, 4
	s_cmp_lt_u32 s2, s92
	s_cbranch_scc0 .Llx1_n3
	global_load_ushort v101, v[116:117], off
.Llx1_n3:
	s_add_i32 s2, s2, 4
	v_add_co_u32_e32 v116, vcc, 0x2000, v116
	s_nop 1
	v_addc_co_u32_e32 v117, vcc, 0, v117, vcc
	s_cmp_lt_u32 s2, s92
	s_cbranch_scc0 .Llx1_n4
	global_load_ushort v102, v[116:117], off offset:-4096
.Llx1_n4:
	s_add_i32 s2, s2, 4
	s_cmp_lt_u32 s2, s92
	s_cbranch_scc0 .Llx1_n5
	global_load_ushort v103, v[116:117], off
.Llx1_n5:
	s_add_i32 s2, s2, 4
	v_add_co_u32_e32 v116, vcc, 0x2000, v116
	s_nop 1
	v_addc_co_u32_e32 v117, vcc, 0, v117, vcc
	s_cmp_lt_u32 s2, s92
	s_cbranch_scc0 .Llx1_n6
	global_load_ushort v104, v[116:117], off offset:-4096
.Llx1_n6:
	s_add_i32 s2, s2, 4
	s_cmp_lt_u32 s2, s92
	s_cbranch_scc0 .Llx1_n7
	global_load_ushort v105, v[116:117], off
.Llx1_n7:
	s_add_i32 s2, s2, 4
	v_add_co_u32_e32 v116, vcc, 0x2000, v116
	s_nop 1
	v_addc_co_u32_e32 v117, vcc, 0, v117, vcc
	s_cmp_lt_u32 s2, s92
	s_cbranch_scc0 .Llx1_n8
	global_load_ushort v106, v[116:117], off offset:-4096
.Llx1_n8:
	s_add_i32 s2, s2, 4
	s_cmp_lt_u32 s2, s92
	s_cbranch_scc0 .Llx1_n9
	global_load_ushort v107, v[116:117], off
.Llx1_n9:
	s_add_i32 s2, s2, 4
	v_add_co_u32_e32 v116, vcc, 0x2000, v116
	s_nop 1
	v_addc_co_u32_e32 v117, vcc, 0, v117, vcc
	s_cmp_lt_u32 s2, s92
	s_cbranch_scc0 .Llx1_n10
	global_load_ushort v108, v[116:117], off offset:-4096
.Llx1_n10:
	s_add_i32 s2, s2, 4
	s_cmp_lt_u32 s2, s92
	s_cbranch_scc0 .Llx1_n11
	global_load_ushort v109, v[116:117], off
.Llx1_n11:
	s_add_i32 s2, s2, 4
	v_add_co_u32_e32 v116, vcc, 0x2000, v116
	s_nop 1
	v_addc_co_u32_e32 v117, vcc, 0, v117, vcc
	s_cmp_lt_u32 s2, s92
	s_cbranch_scc0 .Llx1_n12
	global_load_ushort v110, v[116:117], off offset:-4096
.Llx1_n12:
	s_add_i32 s2, s2, 4
	s_cmp_lt_u32 s2, s92
	s_cbranch_scc0 .Llx1_n13
	global_load_ushort v111, v[116:117], off
.Llx1_n13:
	s_add_i32 s2, s2, 4
	v_add_co_u32_e32 v116, vcc, 0x2000, v116
	s_nop 1
	v_addc_co_u32_e32 v117, vcc, 0, v117, vcc
	s_cmp_lt_u32 s2, s92
	s_cbranch_scc0 .Llx1_n14
	global_load_ushort v112, v[116:117], off offset:-4096
.Llx1_n14:
	s_add_i32 s2, s2, 4
	s_cmp_lt_u32 s2, s92
	s_cbranch_scc0 .Llx1_n15
	global_load_ushort v113, v[116:117], off
.Llx1_n15:
	s_add_i32 s2, s2, 4
	v_add_co_u32_e32 v116, vcc, 0x2000, v116
	s_nop 1
	v_addc_co_u32_e32 v117, vcc, 0, v117, vcc
	s_cmp_lt_u32 s47, 3
	s_cbranch_scc0 .Llx1_n16
	s_cmp_lt_u32 s2, s92
	s_cbranch_scc0 .Llx1_n16
	global_load_ushort v114, v[116:117], off offset:-4096
.Llx1_n16:
	s_add_i32 s2, s2, 4
	s_waitcnt vmcnt(0)
	v_lshl_add_u32 v118, v72, 2, v169
	v_lshl_add_u32 v118, v78, 8, v118
	v_lshlrev_b32_e32 v98, 16, v98
	ds_write_b32 v118, v98
	v_lshlrev_b32_e32 v99, 16, v99
	ds_write_b32 v118, v99 offset:1024
	v_lshlrev_b32_e32 v100, 16, v100
	ds_write_b32 v118, v100 offset:2048
	v_lshlrev_b32_e32 v101, 16, v101
	ds_write_b32 v118, v101 offset:3072
	v_lshlrev_b32_e32 v102, 16, v102
	ds_write_b32 v118, v102 offset:4096
	v_lshlrev_b32_e32 v103, 16, v103
	ds_write_b32 v118, v103 offset:5120
	v_lshlrev_b32_e32 v104, 16, v104
	ds_write_b32 v118, v104 offset:6144
	v_lshlrev_b32_e32 v105, 16, v105
	ds_write_b32 v118, v105 offset:7168
	v_lshlrev_b32_e32 v106, 16, v106
	ds_write_b32 v118, v106 offset:8192
	v_lshlrev_b32_e32 v107, 16, v107
	ds_write_b32 v118, v107 offset:9216
	v_lshlrev_b32_e32 v108, 16, v108
	ds_write_b32 v118, v108 offset:10240
	v_lshlrev_b32_e32 v109, 16, v109
	ds_write_b32 v118, v109 offset:11264
	v_lshlrev_b32_e32 v110, 16, v110
	ds_write_b32 v118, v110 offset:12288
	v_lshlrev_b32_e32 v111, 16, v111
	ds_write_b32 v118, v111 offset:13312
	v_lshlrev_b32_e32 v112, 16, v112
	ds_write_b32 v118, v112 offset:14336
	v_lshlrev_b32_e32 v113, 16, v113
	ds_write_b32 v118, v113 offset:15360
	s_cmp_lt_u32 s47, 3
	s_cbranch_scc0 .Llx1_done
	v_lshlrev_b32_e32 v114, 16, v114
	ds_write_b32 v118, v114 offset:16384
